# attention A2 unit: V fragment LDS reads issued after the QK MFMAs (replacing hazard padding) instead of in front of them, on top of v136
# speedup vs baseline: 1.0063x; 1.0063x over previous
.LBB0_544:
	s_and_b32 s23, s18, 1
	s_cmp_lt_i32 s18, s20
	s_cselect_b64 s[12:13], -1, 0
	s_cmp_gt_i32 s18, s19
	s_cselect_b64 s[36:37], -1, 0
	s_or_b64 s[12:13], s[12:13], s[36:37]
	s_and_b64 vcc, exec, s[12:13]
	s_cbranch_vccnz .LBB0_550
	s_mul_i32 s12, s23, 0x2400
	v_add_u32_e32 v0, s12, v207
	ds_read_b128 v[154:157], v0
	ds_read_b128 v[142:145], v0 offset:32
	ds_read_b128 v[158:161], v0 offset:4608
	ds_read_b128 v[146:149], v0 offset:4640
	ds_read_b128 v[138:141], v0 offset:64
	ds_read_b128 v[134:137], v0 offset:96
	ds_read_b128 v[150:153], v0 offset:4672
	ds_read_b128 v[130:133], v0 offset:4704
	v_add_u32_e32 v0, s12, v204
	v_add_u32_e32 v230, s12, v204
	s_add_i32 s12, s21, s22
	s_cmpk_gt_i32 s12, 0x7f
	s_mov_b64 s[12:13], -1
	s_cbranch_scc1 .LBB0_547
	v_add_u32_e32 v0, s22, v211
	v_add_u32_e32 v34, 63, v0
	v_add_u32_e32 v36, 62, v0
	v_add_u32_e32 v38, 61, v0
	v_add_u32_e32 v40, 60, v0
	v_med3_i32 v35, v34, s53, v235
	v_med3_i32 v34, v34, s95, v237
	v_med3_i32 v37, v36, s53, v235
	v_med3_i32 v36, v36, s95, v237
	v_med3_i32 v39, v38, s53, v235
	v_med3_i32 v38, v38, s95, v237
	v_med3_i32 v41, v40, s53, v235
	v_med3_i32 v40, v40, s95, v237
	v_lshl_add_u32 v35, v35, 2, s39
	v_lshl_add_u32 v34, v34, 2, s39
	v_lshl_add_u32 v37, v37, 2, s39
	v_lshl_add_u32 v36, v36, 2, s39
	v_lshl_add_u32 v38, v38, 2, s39
	v_lshl_add_u32 v40, v40, 2, s39
	v_lshl_add_u32 v39, v39, 2, s39
	v_lshl_add_u32 v41, v41, 2, s39
	ds_read_b32 v50, v35 offset:512
	ds_read_b32 v34, v34 offset:384
	ds_read_b32 v51, v37 offset:512
	ds_read_b32 v35, v36 offset:384
	ds_read_b32 v52, v39 offset:512
	ds_read_b32 v36, v38 offset:384
	ds_read_b32 v53, v41 offset:512
	ds_read_b32 v37, v40 offset:384
	v_add_u32_e32 v38, 55, v0
	v_add_u32_e32 v40, 54, v0
	v_add_u32_e32 v42, 53, v0
	v_add_u32_e32 v44, 52, v0
	v_med3_i32 v39, v38, s53, v235
	v_med3_i32 v38, v38, s95, v237
	v_med3_i32 v41, v40, s53, v235
	v_med3_i32 v40, v40, s95, v237
	v_med3_i32 v43, v42, s53, v235
	v_med3_i32 v42, v42, s95, v237
	v_med3_i32 v45, v44, s53, v235
	v_med3_i32 v44, v44, s95, v237
	v_lshl_add_u32 v39, v39, 2, s39
	v_lshl_add_u32 v38, v38, 2, s39
	v_lshl_add_u32 v41, v41, 2, s39
	v_lshl_add_u32 v40, v40, 2, s39
	v_lshl_add_u32 v42, v42, 2, s39
	v_lshl_add_u32 v44, v44, 2, s39
	v_lshl_add_u32 v43, v43, 2, s39
	v_lshl_add_u32 v45, v45, 2, s39
	ds_read_b32 v54, v39 offset:512
	ds_read_b32 v38, v38 offset:384
	ds_read_b32 v55, v41 offset:512
	ds_read_b32 v39, v40 offset:384
	ds_read_b32 v56, v43 offset:512
	ds_read_b32 v40, v42 offset:384
	ds_read_b32 v57, v45 offset:512
	ds_read_b32 v41, v44 offset:384
	v_add_u32_e32 v42, 47, v0
	v_add_u32_e32 v44, 46, v0
	v_add_u32_e32 v46, 45, v0
	v_add_u32_e32 v48, 44, v0
	v_med3_i32 v43, v42, s53, v235
	v_med3_i32 v42, v42, s95, v237
	v_med3_i32 v45, v44, s53, v235
	v_med3_i32 v44, v44, s95, v237
	v_med3_i32 v47, v46, s53, v235
	v_med3_i32 v46, v46, s95, v237
	v_med3_i32 v49, v48, s53, v235
	v_med3_i32 v48, v48, s95, v237
	v_lshl_add_u32 v43, v43, 2, s39
	v_lshl_add_u32 v42, v42, 2, s39
	v_lshl_add_u32 v45, v45, 2, s39
	v_lshl_add_u32 v44, v44, 2, s39
	v_lshl_add_u32 v46, v46, 2, s39
	v_lshl_add_u32 v48, v48, 2, s39
	v_lshl_add_u32 v47, v47, 2, s39
	v_lshl_add_u32 v49, v49, 2, s39
	ds_read_b32 v58, v43 offset:512
	ds_read_b32 v42, v42 offset:384
	ds_read_b32 v59, v45 offset:512
	ds_read_b32 v43, v44 offset:384
	ds_read_b32 v60, v47 offset:512
	ds_read_b32 v44, v46 offset:384
	ds_read_b32 v61, v49 offset:512
	ds_read_b32 v45, v48 offset:384
	v_add_u32_e32 v46, 39, v0
	v_add_u32_e32 v48, 38, v0
	v_add_u32_e32 v62, 37, v0
	v_med3_i32 v47, v46, s53, v235
	v_med3_i32 v46, v46, s95, v237
	v_med3_i32 v49, v48, s53, v235
	v_med3_i32 v48, v48, s95, v237
	v_med3_i32 v63, v62, s53, v235
	v_med3_i32 v62, v62, s95, v237
	v_add_u32_e32 v0, 36, v0
	v_lshl_add_u32 v47, v47, 2, s39
	v_lshl_add_u32 v46, v46, 2, s39
	v_lshl_add_u32 v49, v49, 2, s39
	v_lshl_add_u32 v48, v48, 2, s39
	v_lshl_add_u32 v64, v63, 2, s39
	v_lshl_add_u32 v65, v62, 2, s39
	v_med3_i32 v62, v0, s53, v235
	v_med3_i32 v0, v0, s95, v237
	v_lshl_add_u32 v201, v62, 2, s39
	v_lshl_add_u32 v0, v0, 2, s39
	ds_read_b32 v62, v47 offset:512
	ds_read_b32 v46, v46 offset:384
	ds_read_b32 v63, v49 offset:512
	ds_read_b32 v47, v48 offset:384
	ds_read_b32 v64, v64 offset:512
	ds_read_b32 v48, v65 offset:384
	ds_read_b32 v65, v201 offset:512
	ds_read_b32 v49, v0 offset:384
	s_mov_b64 s[12:13], 0

.LBB0_549:
	s_waitcnt lgkmcnt(1)
	s_nop 0
	v_mfma_f32_32x32x16_bf16 v[50:65], v[154:157], v[74:77], v[50:65]
	s_waitcnt lgkmcnt(0)
	v_mfma_f32_32x32x16_bf16 v[34:49], v[158:161], v[74:77], v[34:49]
	v_mfma_f32_32x32x16_bf16 v[50:65], v[142:145], v[78:81], v[50:65]
	v_mfma_f32_32x32x16_bf16 v[34:49], v[146:149], v[78:81], v[34:49]
	v_mfma_f32_32x32x16_bf16 v[50:65], v[138:141], v[82:85], v[50:65]
	v_mfma_f32_32x32x16_bf16 v[34:49], v[150:153], v[82:85], v[34:49]
	v_mfma_f32_32x32x16_bf16 v[50:65], v[134:137], v[86:89], v[50:65]
	v_mfma_f32_32x32x16_bf16 v[34:49], v[130:133], v[86:89], v[34:49]
	ds_read_b64_tr_b16 v[126:127], v230 offset:18432
	ds_read_b64_tr_b16 v[128:129], v230 offset:19584
	ds_read_b64_tr_b16 v[124:125], v230 offset:19648
	ds_read_b64_tr_b16 v[122:123], v230 offset:18496
	ds_read_b64_tr_b16 v[118:119], v230 offset:20736
	ds_read_b64_tr_b16 v[120:121], v230 offset:21888
	ds_read_b64_tr_b16 v[116:117], v230 offset:21952
	ds_read_b64_tr_b16 v[114:115], v230 offset:20800
	ds_read_b64_tr_b16 v[110:111], v230 offset:23040
	ds_read_b64_tr_b16 v[112:113], v230 offset:24192
	ds_read_b64_tr_b16 v[108:109], v230 offset:24256
	ds_read_b64_tr_b16 v[106:107], v230 offset:23104
	ds_read_b64_tr_b16 v[102:103], v230 offset:25344
	ds_read_b64_tr_b16 v[104:105], v230 offset:26496
	ds_read_b64_tr_b16 v[100:101], v230 offset:26560
	ds_read_b64_tr_b16 v[98:99], v230 offset:25408
	v_exp_f32_e32 v134, v50
	v_exp_f32_e32 v133, v58
	v_exp_f32_e32 v58, v59
	v_exp_f32_e32 v130, v34
	v_exp_f32_e32 v34, v51
	v_exp_f32_e32 v0, v35
	v_exp_f32_e32 v131, v36
	v_add_f32_e32 v35, v134, v130
	v_exp_f32_e32 v36, v53
	v_pk_add_f32 v[50:51], v[34:35], v[0:1]
	v_exp_f32_e32 v35, v52
	v_pk_add_f32 v[50:51], v[50:51], v[50:51] op_sel_hi:[0,1]
	v_exp_f32_e32 v50, v37
	v_cvt_pk_bf16_f32 v34, v134, v34
	v_add_f32_e32 v37, v35, v131
	v_cvt_pk_bf16_f32 v35, v35, v36
	v_pk_add_f32 v[52:53], v[36:37], v[50:51]
	v_exp_f32_e32 v37, v54
	v_pk_add_f32 v[52:53], v[52:53], v[52:53] op_sel_hi:[0,1]
	v_exp_f32_e32 v51, v38
	v_exp_f32_e32 v38, v55
	v_exp_f32_e32 v52, v39
	v_exp_f32_e32 v132, v40
	v_add_f32_e32 v39, v37, v51
	v_cvt_pk_bf16_f32 v36, v37, v38
	v_pk_add_f32 v[54:55], v[38:39], v[52:53]
	v_exp_f32_e32 v53, v56
	v_exp_f32_e32 v56, v57
	v_pk_add_f32 v[54:55], v[54:55], v[54:55] op_sel_hi:[0,1]
	v_exp_f32_e32 v54, v41
	v_add_f32_e32 v57, v53, v132
	v_cvt_pk_bf16_f32 v37, v53, v56
	v_exp_f32_e32 v53, v42
	v_cvt_pk_bf16_f32 v38, v133, v58
	s_waitcnt lgkmcnt(0)
	v_mfma_f32_32x32x16_bf16 v[2:17], v[34:37], v[126:129], v[2:17]
	v_exp_f32_e32 v126, v60
	v_exp_f32_e32 v60, v61
	v_exp_f32_e32 v127, v62
	v_exp_f32_e32 v62, v63
	v_exp_f32_e32 v128, v64
	v_exp_f32_e32 v64, v65
	v_add_f32_e32 v59, v133, v53
	v_mfma_f32_32x32x16_bf16 v[18:33], v[34:37], v[122:125], v[18:33]
	v_add_f32_e64 v34, v56, v54
	v_add_f32_e64 v35, v57, v55
	v_cvt_pk_bf16_f32 v39, v126, v60
	v_add_f32_e64 v56, v34, v34
	v_add_f32_e64 v57, v34, v35
	v_exp_f32_e32 v56, v43
	v_cvt_pk_bf16_f32 v40, v127, v62
	v_cvt_pk_bf16_f32 v41, v128, v64
	v_exp_f32_e32 v55, v44
	v_pk_add_f32 v[34:35], v[58:59], v[56:57]
	v_mfma_f32_32x32x16_bf16 v[2:17], v[38:41], v[118:121], v[2:17]
	v_add_f32_e64 v42, v34, v34
	v_add_f32_e64 v43, v34, v35
	v_exp_f32_e32 v42, v45
	v_add_f32_e32 v61, v126, v55
	v_cvt_pk_bf16_f32 v34, v130, v0
	v_exp_f32_e32 v0, v46
	v_cvt_pk_bf16_f32 v35, v131, v50
	v_cvt_pk_bf16_f32 v36, v51, v52
	v_mfma_f32_32x32x16_bf16 v[18:33], v[38:41], v[114:117], v[18:33]
	v_add_f32_e64 v38, v60, v42
	v_add_f32_e64 v39, v61, v43
	v_cvt_pk_bf16_f32 v37, v132, v54
	v_add_f32_e64 v40, v38, v38
	v_add_f32_e64 v41, v38, v39
	v_exp_f32_e32 v40, v47
	v_add_f32_e32 v63, v127, v0
	v_exp_f32_e32 v43, v48
	v_pk_add_f32 v[38:39], v[62:63], v[40:41]
	s_nop 0
	v_pk_add_f32 v[44:45], v[38:39], v[38:39] op_sel_hi:[0,1]
	v_exp_f32_e32 v44, v49
	v_mfma_f32_32x32x16_bf16 v[2:17], v[34:37], v[110:113], v[2:17]
	v_cvt_pk_bf16_f32 v38, v53, v56
	v_cvt_pk_bf16_f32 v39, v55, v42
	v_cvt_pk_bf16_f32 v40, v0, v40
	v_cvt_pk_bf16_f32 v41, v43, v44
	v_add_f32_e32 v65, v128, v43
	v_mfma_f32_32x32x16_bf16 v[18:33], v[34:37], v[106:109], v[18:33]
	v_add_f32_e64 v34, v64, v44
	v_add_f32_e64 v35, v65, v45
	v_add_f32_e32 v0, v34, v35
	v_add_f32_e32 v210, v210, v0
	v_mfma_f32_32x32x16_bf16 v[2:17], v[38:41], v[102:105], v[2:17]
	v_mfma_f32_32x32x16_bf16 v[18:33], v[38:41], v[98:101], v[18:33]
